# P9 round 2 as split-K over CU pairs (c, c+128): partner computes K 2048..4095, parks an f32 partial tile in dead ws, then runs the overlapped final norm on 8 waves; c adds the partial before its epilo
# speedup vs baseline: 1.0069x; 1.0052x over previous
.LBB0_952:
	s_cmp_eq_u32 s100, 9
	s_cbranch_scc1 .Lp9_stage_b
	s_mov_b32 s100, 0
	s_mov_b32 s96, 0
	s_movk_i32 s91, 60
	s_movk_i32 s97, 61
	s_mov_b32 s98, s101
	s_movk_i32 s99, 0x200
	s_branch .Lp9_gate
.Lp9_stage_b:
	s_mov_b32 s100, 10
	s_movk_i32 s91, 28
	s_movk_i32 s97, 29
	s_cmpk_lt_u32 s101, 0x80
	s_cbranch_scc0 .Lp9_hi
	s_mov_b32 s96, 1
	s_add_u32 s4, s78, 0x8000000
	s_addc_u32 s5, s79, 0
	s_add_i32 s98, s101, 0x200
	s_movk_i32 s99, 0x280
	s_branch .Lp9_body
.Lp9_hi:
	s_mov_b32 s96, 2
	s_add_u32 s4, s78, 0x8001000
	s_addc_u32 s5, s79, 0
	s_add_u32 s74, s74, 0x1000
	s_addc_u32 s75, s75, 0
	s_add_i32 s98, s101, 0x180
	s_movk_i32 s99, 0x280
	s_branch .Lp9_body
.Lp9_hi_store:
	s_nop 7
	s_nop 7
	s_nop 7
	s_sub_i32 s32, s98, 0x200
	s_lshl_b32 s86, s32, 18
	s_add_u32 s86, s86, 0x1c000000
	s_add_u32 s86, s78, s86
	s_addc_u32 s87, s79, 0
	v_lshlrev_b32_e32 v80, 4, v210
	global_store_dwordx4 v80, v[0:3], s[86:87]
	s_add_u32 s86, s86, 0x2000
	s_addc_u32 s87, s87, 0
	global_store_dwordx4 v80, v[4:7], s[86:87]
	s_add_u32 s86, s86, 0x2000
	s_addc_u32 s87, s87, 0
	global_store_dwordx4 v80, v[8:11], s[86:87]
	s_add_u32 s86, s86, 0x2000
	s_addc_u32 s87, s87, 0
	global_store_dwordx4 v80, v[12:15], s[86:87]
	s_add_u32 s86, s86, 0x2000
	s_addc_u32 s87, s87, 0
	global_store_dwordx4 v80, v[16:19], s[86:87]
	s_add_u32 s86, s86, 0x2000
	s_addc_u32 s87, s87, 0
	global_store_dwordx4 v80, v[20:23], s[86:87]
	s_add_u32 s86, s86, 0x2000
	s_addc_u32 s87, s87, 0
	global_store_dwordx4 v80, v[24:27], s[86:87]
	s_add_u32 s86, s86, 0x2000
	s_addc_u32 s87, s87, 0
	global_store_dwordx4 v80, v[28:31], s[86:87]
	s_add_u32 s86, s86, 0x2000
	s_addc_u32 s87, s87, 0
	global_store_dwordx4 v80, v[32:35], s[86:87]
	s_add_u32 s86, s86, 0x2000
	s_addc_u32 s87, s87, 0
	global_store_dwordx4 v80, v[36:39], s[86:87]
	s_add_u32 s86, s86, 0x2000
	s_addc_u32 s87, s87, 0
	global_store_dwordx4 v80, v[40:43], s[86:87]
	s_add_u32 s86, s86, 0x2000
	s_addc_u32 s87, s87, 0
	global_store_dwordx4 v80, v[44:47], s[86:87]
	s_add_u32 s86, s86, 0x2000
	s_addc_u32 s87, s87, 0
	global_store_dwordx4 v80, v[48:51], s[86:87]
	s_add_u32 s86, s86, 0x2000
	s_addc_u32 s87, s87, 0
	global_store_dwordx4 v80, v[52:55], s[86:87]
	s_add_u32 s86, s86, 0x2000
	s_addc_u32 s87, s87, 0
	global_store_dwordx4 v80, v[56:59], s[86:87]
	s_add_u32 s86, s86, 0x2000
	s_addc_u32 s87, s87, 0
	global_store_dwordx4 v80, v[60:63], s[86:87]
	s_add_u32 s86, s86, 0x2000
	s_addc_u32 s87, s87, 0
	global_store_dwordx4 v80, v[64:67], s[86:87]
	s_add_u32 s86, s86, 0x2000
	s_addc_u32 s87, s87, 0
	global_store_dwordx4 v80, v[68:71], s[86:87]
	s_add_u32 s86, s86, 0x2000
	s_addc_u32 s87, s87, 0
	global_store_dwordx4 v80, v[72:75], s[86:87]
	s_add_u32 s86, s86, 0x2000
	s_addc_u32 s87, s87, 0
	global_store_dwordx4 v80, v[76:79], s[86:87]
	s_add_u32 s86, s86, 0x2000
	s_addc_u32 s87, s87, 0
	global_store_dwordx4 v80, v[96:99], s[86:87]
	s_add_u32 s86, s86, 0x2000
	s_addc_u32 s87, s87, 0
	global_store_dwordx4 v80, v[100:103], s[86:87]
	s_add_u32 s86, s86, 0x2000
	s_addc_u32 s87, s87, 0
	global_store_dwordx4 v80, v[104:107], s[86:87]
	s_add_u32 s86, s86, 0x2000
	s_addc_u32 s87, s87, 0
	global_store_dwordx4 v80, v[108:111], s[86:87]
	s_add_u32 s86, s86, 0x2000
	s_addc_u32 s87, s87, 0
	global_store_dwordx4 v80, v[112:115], s[86:87]
	s_add_u32 s86, s86, 0x2000
	s_addc_u32 s87, s87, 0
	global_store_dwordx4 v80, v[116:119], s[86:87]
	s_add_u32 s86, s86, 0x2000
	s_addc_u32 s87, s87, 0
	global_store_dwordx4 v80, v[120:123], s[86:87]
	s_add_u32 s86, s86, 0x2000
	s_addc_u32 s87, s87, 0
	global_store_dwordx4 v80, v[124:127], s[86:87]
	s_add_u32 s86, s86, 0x2000
	s_addc_u32 s87, s87, 0
	global_store_dwordx4 v80, v[128:131], s[86:87]
	s_add_u32 s86, s86, 0x2000
	s_addc_u32 s87, s87, 0
	global_store_dwordx4 v80, v[132:135], s[86:87]
	s_add_u32 s86, s86, 0x2000
	s_addc_u32 s87, s87, 0
	global_store_dwordx4 v80, v[136:139], s[86:87]
	s_add_u32 s86, s86, 0x2000
	s_addc_u32 s87, s87, 0
	global_store_dwordx4 v80, v[140:143], s[86:87]
	s_add_u32 s86, s86, 0x2000
	s_addc_u32 s87, s87, 0
	s_waitcnt vmcnt(0)
	s_barrier
	v_cmp_eq_u32_e32 vcc, 0, v210
	s_and_saveexec_b64 s[84:85], vcc
	s_cbranch_execz .Lp9_hi_fd
	v_readlane_b32 s86, v255, 0
	s_cmp_eq_u32 s86, 0
	s_cbranch_scc1 .Lp9_hi_nowb
	buffer_wbl2 sc1
	s_waitcnt vmcnt(0)
.Lp9_hi_nowb:
	s_lshl_b32 s86, s32, 2
	s_add_i32 s86, s86, 0x1e03900
	v_mov_b32_e32 v82, s86
	v_mov_b32_e32 v81, 1
	s_nop 0
	global_atomic_add v82, v81, s[78:79]
	s_waitcnt vmcnt(0)
.Lp9_hi_fd:
	s_or_b64 exec, exec, s[84:85]
	s_branch .Lp10a

.Lw10d:
	v_readlane_b32 s2, v254, 6
	v_readlane_b32 s3, v254, 7
	v_and_b32_e32 v0, 63, v210
	v_readfirstlane_b32 s0, v210
	v_lshlrev_b32_e32 v1, 3, v0
	v_lshlrev_b32_e32 v2, 4, v0
	v_mov_b32_e32 v3, 0x3a800000
	v_mov_b32_e32 v121, 0x358637bd
	s_lshr_b32 s0, s0, 6
	global_load_dwordx4 v[4:7], v2, s[2:3]
	global_load_dwordx4 v[8:11], v2, s[2:3] offset:1024
	global_load_dwordx4 v[12:15], v2, s[2:3] offset:2048
	global_load_dwordx4 v[16:19], v2, s[2:3] offset:3072
	s_sub_i32 s1, s101, 128
	s_and_b32 s4, s1, 7
	s_lshr_b32 s5, s1, 4
	s_cmp_lt_u32 s4, 4
	s_cselect_b32 s4, 4, 0xff
	s_cmp_eq_u32 s5, s4
	s_cbranch_scc1 .Lp10a_done
	s_and_b32 s4, s1, 7
	s_mul_i32 s4, s4, 20
	s_lshr_b32 s5, s1, 3
	s_add_i32 s4, s4, s5
	s_lshl_b32 s4, s4, 8
	s_cmp_gt_u32 s0, 7
	s_cbranch_scc1 .Lp10a_done
	s_lshl_b32 s5, s0, 5
	s_add_i32 s4, s4, s5
	s_movk_i32 s10, 8
	s_lshl_b32 s5, s4, 11
	s_add_u32 s12, s78, s5
	s_addc_u32 s13, s79, 0
	s_add_u32 s12, s12, 0x2000000
	s_addc_u32 s13, s13, 0
	s_lshl_b32 s5, s4, 12
	s_add_u32 s14, s76, s5
	s_addc_u32 s15, s77, 0

.LBB0_962:
	ds_read_b128 v[80:83], v164
	ds_read_b128 v[84:87], v164 offset:1024
	ds_read_b128 v[88:91], v164 offset:2048
	ds_read_b128 v[92:95], v164 offset:3072
	ds_read_b128 v[158:161], v165
	ds_read_b128 v[170:173], v165 offset:1024
	ds_read_b128 v[174:177], v165 offset:2048
	ds_read_b128 v[178:181], v165 offset:3072
	s_add_u32 s36, s30, 0xfff00080
	s_addc_u32 s37, s31, -1
	s_cmp_eq_u32 s70, s91
	s_cselect_b32 s39, s21, s37
	s_cselect_b32 s38, s66, s36
	s_cselect_b32 s37, s19, s69
	s_cselect_b32 s36, s67, s68
	v_lshl_add_u64 v[220:221], s[30:31], 0, v[150:151]
	s_add_i32 m0, s29, 0xc000
	ds_read_b128 v[182:185], v166
	ds_read_b128 v[186:189], v166 offset:1024
	ds_read_b128 v[190:193], v166 offset:2048
	ds_read_b128 v[194:197], v166 offset:3072
	ds_read_b128 v[198:201], v166 offset:4096
	ds_read_b128 v[202:205], v166 offset:5120
	ds_read_b128 v[206:209], v166 offset:6144
	ds_read_b128 v[216:219], v166 offset:7168
	global_load_lds_dwordx4 v[220:221], off
	v_lshl_add_u64 v[220:221], s[30:31], 0, v[152:153]
	s_add_i32 m0, s29, 0xe000
	s_nop 0
	global_load_lds_dwordx4 v[220:221], off
	s_waitcnt vmcnt(8)
	s_waitcnt lgkmcnt(0)
	s_barrier
	s_setprio 1
	s_waitcnt lgkmcnt(0)
	v_mfma_f32_16x16x32_bf16 v[140:143], v[80:83], v[182:185], v[140:143]
	v_mfma_f32_16x16x32_bf16 v[136:139], v[88:91], v[182:185], v[136:139]
	v_mfma_f32_16x16x32_bf16 v[124:127], v[80:83], v[190:193], v[124:127]
	v_mfma_f32_16x16x32_bf16 v[120:123], v[88:91], v[190:193], v[120:123]
	v_mfma_f32_16x16x32_bf16 v[108:111], v[80:83], v[198:201], v[108:111]
	v_mfma_f32_16x16x32_bf16 v[104:107], v[88:91], v[198:201], v[104:107]
	v_mfma_f32_16x16x32_bf16 v[76:79], v[80:83], v[206:209], v[76:79]
	v_mfma_f32_16x16x32_bf16 v[72:75], v[88:91], v[206:209], v[72:75]
	v_mfma_f32_16x16x32_bf16 v[140:143], v[84:87], v[186:189], v[140:143]
	v_mfma_f32_16x16x32_bf16 v[136:139], v[92:95], v[186:189], v[136:139]
	v_mfma_f32_16x16x32_bf16 v[124:127], v[84:87], v[194:197], v[124:127]
	v_mfma_f32_16x16x32_bf16 v[120:123], v[92:95], v[194:197], v[120:123]
	v_mfma_f32_16x16x32_bf16 v[108:111], v[84:87], v[202:205], v[108:111]
	v_mfma_f32_16x16x32_bf16 v[104:107], v[92:95], v[202:205], v[104:107]
	v_mfma_f32_16x16x32_bf16 v[76:79], v[84:87], v[216:219], v[76:79]
	v_mfma_f32_16x16x32_bf16 v[72:75], v[92:95], v[216:219], v[72:75]
	s_setprio 0
	s_setprio 1
	v_mfma_f32_16x16x32_bf16 v[132:135], v[158:161], v[182:185], v[132:135]
	v_mfma_f32_16x16x32_bf16 v[128:131], v[174:177], v[182:185], v[128:131]
	v_mfma_f32_16x16x32_bf16 v[116:119], v[158:161], v[190:193], v[116:119]
	v_mfma_f32_16x16x32_bf16 v[112:115], v[174:177], v[190:193], v[112:115]
	v_mfma_f32_16x16x32_bf16 v[100:103], v[158:161], v[198:201], v[100:103]
	v_mfma_f32_16x16x32_bf16 v[96:99], v[174:177], v[198:201], v[96:99]
	v_mfma_f32_16x16x32_bf16 v[68:71], v[158:161], v[206:209], v[68:71]
	v_mfma_f32_16x16x32_bf16 v[64:67], v[174:177], v[206:209], v[64:67]
	v_mfma_f32_16x16x32_bf16 v[132:135], v[170:173], v[186:189], v[132:135]
	v_mfma_f32_16x16x32_bf16 v[128:131], v[178:181], v[186:189], v[128:131]
	v_mfma_f32_16x16x32_bf16 v[116:119], v[170:173], v[194:197], v[116:119]
	v_mfma_f32_16x16x32_bf16 v[112:115], v[178:181], v[194:197], v[112:115]
	v_mfma_f32_16x16x32_bf16 v[100:103], v[170:173], v[202:205], v[100:103]
	v_mfma_f32_16x16x32_bf16 v[96:99], v[178:181], v[202:205], v[96:99]
	v_mfma_f32_16x16x32_bf16 v[68:71], v[170:173], v[216:219], v[68:71]
	v_mfma_f32_16x16x32_bf16 v[64:67], v[178:181], v[216:219], v[64:67]
	s_setprio 0
	s_barrier
	s_add_i32 s71, s53, s3
	v_lshl_add_u64 v[220:221], s[36:37], 0, v[146:147]
	s_mov_b32 m0, s71
	ds_read_b128 v[182:185], v166 offset:16384
	ds_read_b128 v[186:189], v166 offset:17408
	ds_read_b128 v[190:193], v166 offset:18432
	ds_read_b128 v[194:197], v166 offset:19456
	ds_read_b128 v[198:201], v166 offset:20480
	ds_read_b128 v[202:205], v166 offset:21504
	ds_read_b128 v[206:209], v166 offset:22528
	ds_read_b128 v[216:219], v166 offset:23552
	global_load_lds_dwordx4 v[220:221], off
	s_add_i32 m0, s71, 0x2000
	s_add_u32 s72, s36, 0x100000
	v_lshl_add_u64 v[222:223], s[36:37], 0, v[144:145]
	s_addc_u32 s73, s37, 0
	s_add_i32 s71, s54, s3
	global_load_lds_dwordx4 v[222:223], off
	v_lshl_add_u64 v[224:225], s[72:73], 0, v[146:147]
	s_mov_b32 m0, s71
	v_lshl_add_u64 v[226:227], s[38:39], 0, v[144:145]
	global_load_lds_dwordx4 v[224:225], off
	v_lshl_add_u64 v[224:225], s[72:73], 0, v[144:145]
	s_add_i32 m0, s71, 0x2000
	s_nop 0
	global_load_lds_dwordx4 v[224:225], off
	v_lshl_add_u64 v[224:225], s[38:39], 0, v[146:147]
	s_mov_b32 m0, s29
	s_nop 0
	global_load_lds_dwordx4 v[224:225], off
	s_mov_b32 m0, s41
	s_nop 0
	global_load_lds_dwordx4 v[226:227], off
	s_waitcnt vmcnt(8)
	s_waitcnt lgkmcnt(0)
	s_barrier
	s_setprio 1
	s_waitcnt lgkmcnt(0)
	v_mfma_f32_16x16x32_bf16 v[60:63], v[80:83], v[182:185], v[60:63]
	v_mfma_f32_16x16x32_bf16 v[56:59], v[88:91], v[182:185], v[56:59]
	v_mfma_f32_16x16x32_bf16 v[44:47], v[80:83], v[190:193], v[44:47]
	v_mfma_f32_16x16x32_bf16 v[40:43], v[88:91], v[190:193], v[40:43]
	v_mfma_f32_16x16x32_bf16 v[28:31], v[80:83], v[198:201], v[28:31]
	v_mfma_f32_16x16x32_bf16 v[24:27], v[88:91], v[198:201], v[24:27]
	v_mfma_f32_16x16x32_bf16 v[12:15], v[80:83], v[206:209], v[12:15]
	v_mfma_f32_16x16x32_bf16 v[8:11], v[88:91], v[206:209], v[8:11]
	v_mfma_f32_16x16x32_bf16 v[60:63], v[84:87], v[186:189], v[60:63]
	v_mfma_f32_16x16x32_bf16 v[56:59], v[92:95], v[186:189], v[56:59]
	v_mfma_f32_16x16x32_bf16 v[44:47], v[84:87], v[194:197], v[44:47]
	v_mfma_f32_16x16x32_bf16 v[40:43], v[92:95], v[194:197], v[40:43]
	v_mfma_f32_16x16x32_bf16 v[28:31], v[84:87], v[202:205], v[28:31]
	v_mfma_f32_16x16x32_bf16 v[24:27], v[92:95], v[202:205], v[24:27]
	v_mfma_f32_16x16x32_bf16 v[12:15], v[84:87], v[216:219], v[12:15]
	v_mfma_f32_16x16x32_bf16 v[8:11], v[92:95], v[216:219], v[8:11]
	s_setprio 0
	s_setprio 1
	v_mfma_f32_16x16x32_bf16 v[52:55], v[158:161], v[182:185], v[52:55]
	v_mfma_f32_16x16x32_bf16 v[48:51], v[174:177], v[182:185], v[48:51]
	v_mfma_f32_16x16x32_bf16 v[36:39], v[158:161], v[190:193], v[36:39]
	v_mfma_f32_16x16x32_bf16 v[32:35], v[174:177], v[190:193], v[32:35]
	v_mfma_f32_16x16x32_bf16 v[20:23], v[158:161], v[198:201], v[20:23]
	v_mfma_f32_16x16x32_bf16 v[16:19], v[174:177], v[198:201], v[16:19]
	v_mfma_f32_16x16x32_bf16 v[4:7], v[158:161], v[206:209], v[4:7]
	v_mfma_f32_16x16x32_bf16 v[0:3], v[174:177], v[206:209], v[0:3]
	v_mfma_f32_16x16x32_bf16 v[52:55], v[170:173], v[186:189], v[52:55]
	v_mfma_f32_16x16x32_bf16 v[48:51], v[178:181], v[186:189], v[48:51]
	v_mfma_f32_16x16x32_bf16 v[36:39], v[170:173], v[194:197], v[36:39]
	v_mfma_f32_16x16x32_bf16 v[32:35], v[178:181], v[194:197], v[32:35]
	v_mfma_f32_16x16x32_bf16 v[20:23], v[170:173], v[202:205], v[20:23]
	v_mfma_f32_16x16x32_bf16 v[16:19], v[178:181], v[202:205], v[16:19]
	v_mfma_f32_16x16x32_bf16 v[4:7], v[170:173], v[216:219], v[4:7]
	v_mfma_f32_16x16x32_bf16 v[0:3], v[178:181], v[216:219], v[0:3]
	s_setprio 0
	s_barrier
	s_add_i32 s71, 0, 0x18000
	s_add_i32 s72, 0, 0x1c000
	v_add_u32_e32 v92, s71, v149
	v_add_u32_e32 v169, s72, v149
	ds_read_b128 v[80:83], v92
	ds_read_b128 v[84:87], v92 offset:1024
	ds_read_b128 v[88:91], v92 offset:2048
	ds_read_b128 v[92:95], v92 offset:3072
	ds_read_b128 v[158:161], v169
	ds_read_b128 v[170:173], v169 offset:1024
	ds_read_b128 v[174:177], v169 offset:2048
	ds_read_b128 v[178:181], v169 offset:3072
	s_add_u32 s38, s38, 0x100000
	s_addc_u32 s39, s39, 0
	s_mov_b32 m0, s42
	v_lshl_add_u64 v[228:229], s[38:39], 0, v[146:147]
	ds_read_b128 v[182:185], v166 offset:32768
	ds_read_b128 v[186:189], v166 offset:33792
	ds_read_b128 v[190:193], v166 offset:34816
	ds_read_b128 v[194:197], v166 offset:35840
	ds_read_b128 v[198:201], v166 offset:36864
	ds_read_b128 v[202:205], v166 offset:37888
	ds_read_b128 v[206:209], v166 offset:38912
	ds_read_b128 v[216:219], v166 offset:39936
	global_load_lds_dwordx4 v[228:229], off
	v_lshl_add_u64 v[228:229], s[38:39], 0, v[144:145]
	s_mov_b32 m0, s43
	s_nop 0
	global_load_lds_dwordx4 v[228:229], off
	s_waitcnt vmcnt(8)
	s_waitcnt lgkmcnt(0)
	s_barrier
	s_setprio 1
	s_waitcnt lgkmcnt(0)
	v_mfma_f32_16x16x32_bf16 v[140:143], v[80:83], v[182:185], v[140:143]
	v_mfma_f32_16x16x32_bf16 v[136:139], v[88:91], v[182:185], v[136:139]
	v_mfma_f32_16x16x32_bf16 v[124:127], v[80:83], v[190:193], v[124:127]
	v_mfma_f32_16x16x32_bf16 v[120:123], v[88:91], v[190:193], v[120:123]
	v_mfma_f32_16x16x32_bf16 v[108:111], v[80:83], v[198:201], v[108:111]
	v_mfma_f32_16x16x32_bf16 v[104:107], v[88:91], v[198:201], v[104:107]
	v_mfma_f32_16x16x32_bf16 v[76:79], v[80:83], v[206:209], v[76:79]
	v_mfma_f32_16x16x32_bf16 v[72:75], v[88:91], v[206:209], v[72:75]
	v_mfma_f32_16x16x32_bf16 v[140:143], v[84:87], v[186:189], v[140:143]
	v_mfma_f32_16x16x32_bf16 v[136:139], v[92:95], v[186:189], v[136:139]
	v_mfma_f32_16x16x32_bf16 v[124:127], v[84:87], v[194:197], v[124:127]
	v_mfma_f32_16x16x32_bf16 v[120:123], v[92:95], v[194:197], v[120:123]
	v_mfma_f32_16x16x32_bf16 v[108:111], v[84:87], v[202:205], v[108:111]
	v_mfma_f32_16x16x32_bf16 v[104:107], v[92:95], v[202:205], v[104:107]
	v_mfma_f32_16x16x32_bf16 v[76:79], v[84:87], v[216:219], v[76:79]
	v_mfma_f32_16x16x32_bf16 v[72:75], v[92:95], v[216:219], v[72:75]
	s_setprio 0
	s_setprio 1
	v_mfma_f32_16x16x32_bf16 v[132:135], v[158:161], v[182:185], v[132:135]
	v_mfma_f32_16x16x32_bf16 v[128:131], v[174:177], v[182:185], v[128:131]
	v_mfma_f32_16x16x32_bf16 v[116:119], v[158:161], v[190:193], v[116:119]
	v_mfma_f32_16x16x32_bf16 v[112:115], v[174:177], v[190:193], v[112:115]
	v_mfma_f32_16x16x32_bf16 v[100:103], v[158:161], v[198:201], v[100:103]
	v_mfma_f32_16x16x32_bf16 v[96:99], v[174:177], v[198:201], v[96:99]
	v_mfma_f32_16x16x32_bf16 v[68:71], v[158:161], v[206:209], v[68:71]
	v_mfma_f32_16x16x32_bf16 v[64:67], v[174:177], v[206:209], v[64:67]
	v_mfma_f32_16x16x32_bf16 v[132:135], v[170:173], v[186:189], v[132:135]
	v_mfma_f32_16x16x32_bf16 v[128:131], v[178:181], v[186:189], v[128:131]
	v_mfma_f32_16x16x32_bf16 v[116:119], v[170:173], v[194:197], v[116:119]
	v_mfma_f32_16x16x32_bf16 v[112:115], v[178:181], v[194:197], v[112:115]
	v_mfma_f32_16x16x32_bf16 v[100:103], v[170:173], v[202:205], v[100:103]
	v_mfma_f32_16x16x32_bf16 v[96:99], v[178:181], v[202:205], v[96:99]
	v_mfma_f32_16x16x32_bf16 v[68:71], v[170:173], v[216:219], v[68:71]
	v_mfma_f32_16x16x32_bf16 v[64:67], v[178:181], v[216:219], v[64:67]
	s_setprio 0
	s_barrier
	s_add_i32 s38, s71, s3
	v_lshl_add_u64 v[220:221], v[220:221], 0, s[12:13]
	s_mov_b32 m0, s38
	ds_read_b128 v[182:185], v166 offset:49152
	ds_read_b128 v[186:189], v166 offset:50176
	ds_read_b128 v[190:193], v166 offset:51200
	ds_read_b128 v[194:197], v166 offset:52224
	ds_read_b128 v[198:201], v166 offset:53248
	ds_read_b128 v[202:205], v166 offset:54272
	ds_read_b128 v[206:209], v166 offset:55296
	ds_read_b128 v[216:219], v166 offset:56320
	global_load_lds_dwordx4 v[220:221], off
	s_add_i32 m0, s38, 0x2000
	s_add_u32 s36, s36, 0x100080
	v_lshl_add_u64 v[220:221], v[222:223], 0, s[12:13]
	s_addc_u32 s37, s37, 0
	s_add_i32 s38, s72, s3
	global_load_lds_dwordx4 v[220:221], off
	v_lshl_add_u64 v[220:221], s[36:37], 0, v[146:147]
	s_mov_b32 m0, s38
	s_nop 0
	global_load_lds_dwordx4 v[220:221], off
	v_lshl_add_u64 v[220:221], s[36:37], 0, v[144:145]
	s_add_i32 m0, s38, 0x2000
	s_nop 0
	global_load_lds_dwordx4 v[220:221], off
	v_lshl_add_u64 v[220:221], v[224:225], 0, s[12:13]
	s_mov_b32 m0, s47
	s_nop 0
	global_load_lds_dwordx4 v[220:221], off
	v_lshl_add_u64 v[220:221], v[226:227], 0, s[12:13]
	s_mov_b32 m0, s48
	s_nop 0
	global_load_lds_dwordx4 v[220:221], off
	s_waitcnt vmcnt(8)
	s_waitcnt lgkmcnt(0)
	s_barrier
	s_setprio 1
	s_waitcnt lgkmcnt(0)
	v_mfma_f32_16x16x32_bf16 v[60:63], v[80:83], v[182:185], v[60:63]
	v_mfma_f32_16x16x32_bf16 v[56:59], v[88:91], v[182:185], v[56:59]
	v_mfma_f32_16x16x32_bf16 v[44:47], v[80:83], v[190:193], v[44:47]
	v_mfma_f32_16x16x32_bf16 v[40:43], v[88:91], v[190:193], v[40:43]
	v_mfma_f32_16x16x32_bf16 v[28:31], v[80:83], v[198:201], v[28:31]
	v_mfma_f32_16x16x32_bf16 v[24:27], v[88:91], v[198:201], v[24:27]
	v_mfma_f32_16x16x32_bf16 v[12:15], v[80:83], v[206:209], v[12:15]
	v_mfma_f32_16x16x32_bf16 v[8:11], v[88:91], v[206:209], v[8:11]
	v_mfma_f32_16x16x32_bf16 v[60:63], v[84:87], v[186:189], v[60:63]
	v_mfma_f32_16x16x32_bf16 v[56:59], v[92:95], v[186:189], v[56:59]
	v_mfma_f32_16x16x32_bf16 v[44:47], v[84:87], v[194:197], v[44:47]
	v_mfma_f32_16x16x32_bf16 v[40:43], v[92:95], v[194:197], v[40:43]
	v_mfma_f32_16x16x32_bf16 v[28:31], v[84:87], v[202:205], v[28:31]
	v_mfma_f32_16x16x32_bf16 v[24:27], v[92:95], v[202:205], v[24:27]
	v_mfma_f32_16x16x32_bf16 v[12:15], v[84:87], v[216:219], v[12:15]
	v_mfma_f32_16x16x32_bf16 v[8:11], v[92:95], v[216:219], v[8:11]
	s_setprio 0
	s_setprio 1
	v_mfma_f32_16x16x32_bf16 v[52:55], v[158:161], v[182:185], v[52:55]
	v_mfma_f32_16x16x32_bf16 v[48:51], v[174:177], v[182:185], v[48:51]
	v_mfma_f32_16x16x32_bf16 v[36:39], v[158:161], v[190:193], v[36:39]
	v_mfma_f32_16x16x32_bf16 v[32:35], v[174:177], v[190:193], v[32:35]
	v_mfma_f32_16x16x32_bf16 v[20:23], v[158:161], v[198:201], v[20:23]
	v_mfma_f32_16x16x32_bf16 v[16:19], v[174:177], v[198:201], v[16:19]
	v_mfma_f32_16x16x32_bf16 v[4:7], v[158:161], v[206:209], v[4:7]
	v_mfma_f32_16x16x32_bf16 v[0:3], v[174:177], v[206:209], v[0:3]
	v_mfma_f32_16x16x32_bf16 v[52:55], v[170:173], v[186:189], v[52:55]
	v_mfma_f32_16x16x32_bf16 v[48:51], v[178:181], v[186:189], v[48:51]
	v_mfma_f32_16x16x32_bf16 v[36:39], v[170:173], v[194:197], v[36:39]
	v_mfma_f32_16x16x32_bf16 v[32:35], v[178:181], v[194:197], v[32:35]
	v_mfma_f32_16x16x32_bf16 v[20:23], v[170:173], v[202:205], v[20:23]
	v_mfma_f32_16x16x32_bf16 v[16:19], v[178:181], v[202:205], v[16:19]
	v_mfma_f32_16x16x32_bf16 v[4:7], v[170:173], v[216:219], v[4:7]
	v_mfma_f32_16x16x32_bf16 v[0:3], v[178:181], v[216:219], v[0:3]
	s_setprio 0
	s_barrier
	s_add_i32 s70, s70, 2
	s_add_u32 s30, s30, 0x100
	s_addc_u32 s31, s31, 0
	s_add_u32 s68, s68, 0x100
	s_addc_u32 s69, s69, 0
	s_cmp_gt_u32 s70, s97
	s_cbranch_scc0 .LBB0_962
	s_and_b64 vcc, exec, s[14:15]
	s_cbranch_vccz .LBB0_965
	s_barrier
.LBB0_965:
	s_cmp_eq_u32 s96, 2
	s_cbranch_scc1 .Lp9_hi_store
	s_cmp_eq_u32 s96, 1
	s_cbranch_scc0 .Lp9_epi
	s_nop 7
	s_nop 7
	s_nop 7
	s_sub_i32 s32, s98, 0x200
	v_cmp_eq_u32_e32 vcc, 0, v210
	s_and_saveexec_b64 s[84:85], vcc
	s_cbranch_execz .Lp9_lo_pd
	s_lshl_b32 s86, s32, 2
	s_add_i32 s86, s86, 0x1e03900
	v_mov_b32_e32 v82, s86
.Lp9_lo_poll:
	global_load_dword v81, v82, s[78:79] sc1
	s_waitcnt vmcnt(0)
	v_cmp_eq_u32_e32 vcc, 0, v81
	s_cbranch_vccz .Lp9_lo_pd
	s_sleep 2
	s_branch .Lp9_lo_poll
.Lp9_lo_pd:
	s_or_b64 exec, exec, s[84:85]
	s_barrier
	buffer_inv sc1
	s_lshl_b32 s86, s32, 18
	s_add_u32 s86, s86, 0x1c000000
	s_add_u32 s86, s78, s86
	s_addc_u32 s87, s79, 0
	v_lshlrev_b32_e32 v80, 4, v210
	global_load_dwordx4 v[170:173], v80, s[86:87]
	s_add_u32 s86, s86, 0x2000
	s_addc_u32 s87, s87, 0
	global_load_dwordx4 v[174:177], v80, s[86:87]
	s_add_u32 s86, s86, 0x2000
	s_addc_u32 s87, s87, 0
	global_load_dwordx4 v[178:181], v80, s[86:87]
	s_add_u32 s86, s86, 0x2000
	s_addc_u32 s87, s87, 0
	global_load_dwordx4 v[182:185], v80, s[86:87]
	s_add_u32 s86, s86, 0x2000
	s_addc_u32 s87, s87, 0
	global_load_dwordx4 v[186:189], v80, s[86:87]
	s_add_u32 s86, s86, 0x2000
	s_addc_u32 s87, s87, 0
	global_load_dwordx4 v[190:193], v80, s[86:87]
	s_add_u32 s86, s86, 0x2000
	s_addc_u32 s87, s87, 0
	global_load_dwordx4 v[194:197], v80, s[86:87]
	s_add_u32 s86, s86, 0x2000
	s_addc_u32 s87, s87, 0
	global_load_dwordx4 v[198:201], v80, s[86:87]
	s_add_u32 s86, s86, 0x2000
	s_addc_u32 s87, s87, 0
	global_load_dwordx4 v[202:205], v80, s[86:87]
	s_add_u32 s86, s86, 0x2000
	s_addc_u32 s87, s87, 0
	global_load_dwordx4 v[206:209], v80, s[86:87]
	s_add_u32 s86, s86, 0x2000
	s_addc_u32 s87, s87, 0
	global_load_dwordx4 v[216:219], v80, s[86:87]
	s_add_u32 s86, s86, 0x2000
	s_addc_u32 s87, s87, 0
	global_load_dwordx4 v[220:223], v80, s[86:87]
	s_add_u32 s86, s86, 0x2000
	s_addc_u32 s87, s87, 0
	global_load_dwordx4 v[224:227], v80, s[86:87]
	s_add_u32 s86, s86, 0x2000
	s_addc_u32 s87, s87, 0
	global_load_dwordx4 v[84:87], v80, s[86:87]
	s_add_u32 s86, s86, 0x2000
	s_addc_u32 s87, s87, 0
	global_load_dwordx4 v[88:91], v80, s[86:87]
	s_add_u32 s86, s86, 0x2000
	s_addc_u32 s87, s87, 0
	global_load_dwordx4 v[92:95], v80, s[86:87]
	s_add_u32 s86, s86, 0x2000
	s_addc_u32 s87, s87, 0
	s_waitcnt vmcnt(15)
	v_pk_add_f32 v[0:1], v[0:1], v[170:171]
	v_pk_add_f32 v[2:3], v[2:3], v[172:173]
	s_waitcnt vmcnt(14)
	v_pk_add_f32 v[4:5], v[4:5], v[174:175]
	v_pk_add_f32 v[6:7], v[6:7], v[176:177]
	s_waitcnt vmcnt(13)
	v_pk_add_f32 v[8:9], v[8:9], v[178:179]
	v_pk_add_f32 v[10:11], v[10:11], v[180:181]
	s_waitcnt vmcnt(12)
	v_pk_add_f32 v[12:13], v[12:13], v[182:183]
	v_pk_add_f32 v[14:15], v[14:15], v[184:185]
	s_waitcnt vmcnt(11)
	v_pk_add_f32 v[16:17], v[16:17], v[186:187]
	v_pk_add_f32 v[18:19], v[18:19], v[188:189]
	s_waitcnt vmcnt(10)
	v_pk_add_f32 v[20:21], v[20:21], v[190:191]
	v_pk_add_f32 v[22:23], v[22:23], v[192:193]
	s_waitcnt vmcnt(9)
	v_pk_add_f32 v[24:25], v[24:25], v[194:195]
	v_pk_add_f32 v[26:27], v[26:27], v[196:197]
	s_waitcnt vmcnt(8)
	v_pk_add_f32 v[28:29], v[28:29], v[198:199]
	v_pk_add_f32 v[30:31], v[30:31], v[200:201]
	s_waitcnt vmcnt(7)
	v_pk_add_f32 v[32:33], v[32:33], v[202:203]
	v_pk_add_f32 v[34:35], v[34:35], v[204:205]
	s_waitcnt vmcnt(6)
	v_pk_add_f32 v[36:37], v[36:37], v[206:207]
	v_pk_add_f32 v[38:39], v[38:39], v[208:209]
	s_waitcnt vmcnt(5)
	v_pk_add_f32 v[40:41], v[40:41], v[216:217]
	v_pk_add_f32 v[42:43], v[42:43], v[218:219]
	s_waitcnt vmcnt(4)
	v_pk_add_f32 v[44:45], v[44:45], v[220:221]
	v_pk_add_f32 v[46:47], v[46:47], v[222:223]
	s_waitcnt vmcnt(3)
	v_pk_add_f32 v[48:49], v[48:49], v[224:225]
	v_pk_add_f32 v[50:51], v[50:51], v[226:227]
	s_waitcnt vmcnt(2)
	v_pk_add_f32 v[52:53], v[52:53], v[84:85]
	v_pk_add_f32 v[54:55], v[54:55], v[86:87]
	s_waitcnt vmcnt(1)
	v_pk_add_f32 v[56:57], v[56:57], v[88:89]
	v_pk_add_f32 v[58:59], v[58:59], v[90:91]
	s_waitcnt vmcnt(0)
	v_pk_add_f32 v[60:61], v[60:61], v[92:93]
	v_pk_add_f32 v[62:63], v[62:63], v[94:95]
	global_load_dwordx4 v[170:173], v80, s[86:87]
	s_add_u32 s86, s86, 0x2000
	s_addc_u32 s87, s87, 0
	global_load_dwordx4 v[174:177], v80, s[86:87]
	s_add_u32 s86, s86, 0x2000
	s_addc_u32 s87, s87, 0
	global_load_dwordx4 v[178:181], v80, s[86:87]
	s_add_u32 s86, s86, 0x2000
	s_addc_u32 s87, s87, 0
	global_load_dwordx4 v[182:185], v80, s[86:87]
	s_add_u32 s86, s86, 0x2000
	s_addc_u32 s87, s87, 0
	global_load_dwordx4 v[186:189], v80, s[86:87]
	s_add_u32 s86, s86, 0x2000
	s_addc_u32 s87, s87, 0
	global_load_dwordx4 v[190:193], v80, s[86:87]
	s_add_u32 s86, s86, 0x2000
	s_addc_u32 s87, s87, 0
	global_load_dwordx4 v[194:197], v80, s[86:87]
	s_add_u32 s86, s86, 0x2000
	s_addc_u32 s87, s87, 0
	global_load_dwordx4 v[198:201], v80, s[86:87]
	s_add_u32 s86, s86, 0x2000
	s_addc_u32 s87, s87, 0
	global_load_dwordx4 v[202:205], v80, s[86:87]
	s_add_u32 s86, s86, 0x2000
	s_addc_u32 s87, s87, 0
	global_load_dwordx4 v[206:209], v80, s[86:87]
	s_add_u32 s86, s86, 0x2000
	s_addc_u32 s87, s87, 0
	global_load_dwordx4 v[216:219], v80, s[86:87]
	s_add_u32 s86, s86, 0x2000
	s_addc_u32 s87, s87, 0
	global_load_dwordx4 v[220:223], v80, s[86:87]
	s_add_u32 s86, s86, 0x2000
	s_addc_u32 s87, s87, 0
	global_load_dwordx4 v[224:227], v80, s[86:87]
	s_add_u32 s86, s86, 0x2000
	s_addc_u32 s87, s87, 0
	global_load_dwordx4 v[84:87], v80, s[86:87]
	s_add_u32 s86, s86, 0x2000
	s_addc_u32 s87, s87, 0
	global_load_dwordx4 v[88:91], v80, s[86:87]
	s_add_u32 s86, s86, 0x2000
	s_addc_u32 s87, s87, 0
	global_load_dwordx4 v[92:95], v80, s[86:87]
	s_add_u32 s86, s86, 0x2000
	s_addc_u32 s87, s87, 0
	s_waitcnt vmcnt(15)
	v_pk_add_f32 v[64:65], v[64:65], v[170:171]
	v_pk_add_f32 v[66:67], v[66:67], v[172:173]
	s_waitcnt vmcnt(14)
	v_pk_add_f32 v[68:69], v[68:69], v[174:175]
	v_pk_add_f32 v[70:71], v[70:71], v[176:177]
	s_waitcnt vmcnt(13)
	v_pk_add_f32 v[72:73], v[72:73], v[178:179]
	v_pk_add_f32 v[74:75], v[74:75], v[180:181]
	s_waitcnt vmcnt(12)
	v_pk_add_f32 v[76:77], v[76:77], v[182:183]
	v_pk_add_f32 v[78:79], v[78:79], v[184:185]
	s_waitcnt vmcnt(11)
	v_pk_add_f32 v[96:97], v[96:97], v[186:187]
	v_pk_add_f32 v[98:99], v[98:99], v[188:189]
	s_waitcnt vmcnt(10)
	v_pk_add_f32 v[100:101], v[100:101], v[190:191]
	v_pk_add_f32 v[102:103], v[102:103], v[192:193]
	s_waitcnt vmcnt(9)
	v_pk_add_f32 v[104:105], v[104:105], v[194:195]
	v_pk_add_f32 v[106:107], v[106:107], v[196:197]
	s_waitcnt vmcnt(8)
	v_pk_add_f32 v[108:109], v[108:109], v[198:199]
	v_pk_add_f32 v[110:111], v[110:111], v[200:201]
	s_waitcnt vmcnt(7)
	v_pk_add_f32 v[112:113], v[112:113], v[202:203]
	v_pk_add_f32 v[114:115], v[114:115], v[204:205]
	s_waitcnt vmcnt(6)
	v_pk_add_f32 v[116:117], v[116:117], v[206:207]
	v_pk_add_f32 v[118:119], v[118:119], v[208:209]
	s_waitcnt vmcnt(5)
	v_pk_add_f32 v[120:121], v[120:121], v[216:217]
	v_pk_add_f32 v[122:123], v[122:123], v[218:219]
	s_waitcnt vmcnt(4)
	v_pk_add_f32 v[124:125], v[124:125], v[220:221]
	v_pk_add_f32 v[126:127], v[126:127], v[222:223]
	s_waitcnt vmcnt(3)
	v_pk_add_f32 v[128:129], v[128:129], v[224:225]
	v_pk_add_f32 v[130:131], v[130:131], v[226:227]
	s_waitcnt vmcnt(2)
	v_pk_add_f32 v[132:133], v[132:133], v[84:85]
	v_pk_add_f32 v[134:135], v[134:135], v[86:87]
	s_waitcnt vmcnt(1)
	v_pk_add_f32 v[136:137], v[136:137], v[88:89]
	v_pk_add_f32 v[138:139], v[138:139], v[90:91]
	s_waitcnt vmcnt(0)
	v_pk_add_f32 v[140:141], v[140:141], v[92:93]
	v_pk_add_f32 v[142:143], v[142:143], v[94:95]
